# DSA in-projection: 17th (mostly padding) column tile replaced by a split-K mini GEMM for the 80 KI|WI columns run by all 256 workgroups (64 rows each), LDS reduction, same epilogue arithmetic
# speedup vs baseline: 1.0151x; 1.0107x over previous
;     __host__ __device__ bool next(int i, Unit& u) const {
;         const long L = (long)i * G + c; if (L >= nwg) return false;
;         int wgid = (int)L; { const int q = nwg / NXCD, r = nwg % NXCD, xcd = wgid % NXCD, off = wgid / NXCD; wgid = (xcd < r ? xcd * (q + 1) : r * (q + 1) + (xcd - r) * q) + off; }
;         const int nig = WGM * nN, gid = wgid / nig, fm = gid * WGM, gsz = (nM - fm) < WGM ? (nM - fm) : WGM;
;         u.pm = fm + ((wgid % nig) % gsz); u.pn = (wgid % nig) / gsz; return true;
.LBB0_130:
	s_add_i32 s37, s37, 1
	s_mul_i32 s0, s37, s87
	s_mul_hi_u32 s1, s37, s64
	s_add_i32 s1, s1, s0
	s_mul_i32 s0, s37, s64
	s_add_u32 s20, s0, s57
	s_addc_u32 s21, s1, s86
	v_mov_b64_e32 v[0:1], 0x400
	v_cmp_lt_i64_e64 s[0:1], s[20:21], v[0:1]
	v_mov_b64_e32 v[0:1], 0x3ff
	v_cmp_gt_i64_e32 vcc, s[20:21], v[0:1]
	s_cbranch_vccnz .LBB0_132
	s_ashr_i32 s16, s20, 31
	s_lshr_b32 s16, s16, 29
	s_add_i32 s16, s20, s16
	s_ashr_i32 s17, s16, 3
	s_and_b32 s16, s16, -8
	s_sub_i32 s16, s20, s16
	s_cmp_lt_i32 s16, 0
	s_movk_i32 s18, 0x89
	s_cselect_b32 s18, s18, 0x88
	s_mul_i32 s16, s16, s18
	s_add_i32 s16, s16, s17
	s_mul_hi_i32 s17, s16, 0x78787879
	s_lshr_b32 s18, s17, 31
	s_ashr_i32 s17, s17, 6
	s_add_i32 s17, s17, s18
	s_lshl_b32 s18, s17, 3
	s_sub_i32 s19, 64, s18
	s_min_i32 s19, s19, 8
	s_abs_i32 s20, s19
	v_cvt_f32_u32_e32 v0, s20
	s_sub_i32 s22, 0, s20
	s_mulk_i32 s17, 0x88
	s_sub_i32 s17, s16, s17
	v_rcp_iflag_f32_e32 v0, v0
	s_abs_i32 s16, s17
	s_xor_b32 s21, s17, s19
	s_ashr_i32 s21, s21, 31
	v_mul_f32_e32 v0, 0x4f7ffffe, v0
	v_cvt_u32_f32_e32 v0, v0
	s_nop 0
	v_readfirstlane_b32 s23, v0
	s_mul_i32 s22, s22, s23
	s_mul_hi_u32 s22, s23, s22
	s_add_i32 s23, s23, s22
	s_mul_hi_u32 s22, s16, s23
	s_mul_i32 s23, s22, s20
	s_sub_i32 s16, s16, s23
	s_add_i32 s24, s22, 1
	s_sub_i32 s23, s16, s20
	s_cmp_ge_u32 s16, s20
	s_cselect_b32 s22, s24, s22
	s_cselect_b32 s16, s23, s16
	s_add_i32 s23, s22, 1
	s_cmp_ge_u32 s16, s20
	s_cselect_b32 s16, s23, s22
	s_xor_b32 s16, s16, s21
	s_sub_i32 s16, s16, s21
	s_mul_i32 s19, s16, s19
	s_sub_i32 s17, s17, s19
	s_add_i32 s18, s18, s17

; #define PG8_WAIT_V(n) asm volatile("s_waitcnt vmcnt(" #n ")" ::: "memory")
; #define PG8_BAR __builtin_amdgcn_s_barrier()
; template <class Epi, class Sched, bool ALIGN_EPI = false, bool SP2 = false>
; __device__ __forceinline__ void gemm_phase(PG8_LAS unsigned char* lds, const Gemm g, const Sched& S, const Epi& E, const int wid_in) {
;     ...
;     for (int i = 0; i < 2; ++i) { int R, C; stage_rc(tid * 16 + i * 8192, R, C); const int Rb = Epi::PERM ? ((R & ~31) + perm32(R & 31)) : R;
;         voffA[i] = (unsigned)(R * K + C) * 2u; voffB[i] = (unsigned)(Rb * K + C) * 2u; }
;     const size_t kstep = (size_t)(BK * 2);
;     const size_t hstep = (size_t)HALF * K * 2;
;     const size_t tstep = 2 * hstep;
;     const unsigned ldsw = (unsigned)wid * 1024u;
;     const int aoff = lds_byte(wr * 64 + fr, fq * 8), boff = lds_byte(wc * 32 + fr, fq * 8);
;     ...
;     PG8_WAIT_V(0);
;     if constexpr (!ALIGN_EPI) { if (wr == 0) PG8_BAR; }
;     PG8_BAR;
.LBB0_155:
	s_waitcnt vmcnt(0)
	v_readlane_b32 s16, v253, 42
	v_readlane_b32 s17, v253, 43
	s_barrier
	v_lshrrev_b32_e32 v214, 6, v207
	v_and_b32_e32 v215, 15, v206
	v_lshrrev_b32_e32 v216, 4, v206
	v_readfirstlane_b32 s15, v214
	v_lshlrev_b32_e32 v180, 12, v215
	v_lshl_add_u32 v180, v216, 4, v180
	v_lshlrev_b32_e32 v181, 4, v206
	v_readlane_b32 s14, v251, 14
	s_nop 3
.Lmg_unit:
	s_cmpk_ge_u32 s14, 0x100
	s_cbranch_scc1 .Lmg_done
	s_and_b32 s0, s14, 7
	s_lshl_b32 s0, s0, 3
	s_bfe_u32 s1, s14, 0x30003
	s_add_i32 s0, s0, s1
	s_lshr_b32 s1, s14, 6
	s_lshl_b32 s0, s0, 8
	s_lshl_b32 s1, s1, 6
	s_add_i32 s35, s0, s1
	s_and_b32 s0, s15, 3
	s_lshl_b32 s0, s0, 4
	s_add_i32 s0, s0, s35
	v_and_b32_e32 v214, 15, v206
	v_add_u32_e32 v214, s0, v214
	v_lshlrev_b32_e32 v216, 3, v214
	global_load_dwordx2 v[218:219], v216, s[10:11] sc1
	s_lshl_b32 s0, s15, 9
	s_lshl_b32 s4, s35, 12
	s_add_u32 s4, s4, s0
	s_add_u32 s18, s62, 0x17300000
	s_addc_u32 s19, s63, 0
	s_add_u32 s18, s18, s4
	s_addc_u32 s19, s19, 0
	s_add_u32 s20, s18, 0x10000
	s_addc_u32 s21, s19, 0
	s_add_u32 s22, s20, 0x10000
	s_addc_u32 s23, s21, 0
	s_add_u32 s24, s22, 0x10000
	s_addc_u32 s25, s23, 0
	s_add_u32 s36, s26, 0x1000000
	s_addc_u32 s37, s27, 0
	s_add_u32 s36, s36, s0
	s_addc_u32 s37, s37, 0
	s_add_u32 s38, s36, 0x10000
	s_addc_u32 s39, s37, 0
	s_add_u32 s40, s38, 0x10000
	s_addc_u32 s41, s39, 0
	s_add_u32 s42, s40, 0x10000
	s_addc_u32 s43, s41, 0
	s_add_u32 s44, s42, 0x10000
	s_addc_u32 s45, s43, 0
	global_load_dwordx4 v[80:83], v180, s[18:19] offset:0
	global_load_dwordx4 v[84:87], v180, s[20:21] offset:0
	global_load_dwordx4 v[88:91], v180, s[22:23] offset:0
	global_load_dwordx4 v[92:95], v180, s[24:25] offset:0
	global_load_dwordx4 v[96:99], v180, s[36:37] offset:0
	global_load_dwordx4 v[100:103], v180, s[38:39] offset:0
	global_load_dwordx4 v[104:107], v180, s[40:41] offset:0
	global_load_dwordx4 v[108:111], v180, s[42:43] offset:0
	global_load_dwordx4 v[112:115], v180, s[44:45] offset:0
	global_load_dwordx4 v[116:119], v180, s[18:19] offset:64
	global_load_dwordx4 v[120:123], v180, s[20:21] offset:64
	global_load_dwordx4 v[124:127], v180, s[22:23] offset:64
	global_load_dwordx4 v[128:131], v180, s[24:25] offset:64
	global_load_dwordx4 v[132:135], v180, s[36:37] offset:64
	global_load_dwordx4 v[136:139], v180, s[38:39] offset:64
	global_load_dwordx4 v[140:143], v180, s[40:41] offset:64
	global_load_dwordx4 v[144:147], v180, s[42:43] offset:64
	global_load_dwordx4 v[148:151], v180, s[44:45] offset:64
	global_load_dwordx4 v[152:155], v180, s[18:19] offset:128
	global_load_dwordx4 v[156:159], v180, s[20:21] offset:128
	global_load_dwordx4 v[160:163], v180, s[22:23] offset:128
	global_load_dwordx4 v[164:167], v180, s[24:25] offset:128
	global_load_dwordx4 v[168:171], v180, s[36:37] offset:128
	global_load_dwordx4 v[172:175], v180, s[38:39] offset:128
	global_load_dwordx4 v[176:179], v180, s[40:41] offset:128
	global_load_dwordx4 v[188:191], v180, s[42:43] offset:128
	global_load_dwordx4 v[192:195], v180, s[44:45] offset:128
	s_waitcnt vmcnt(18)
	v_mfma_f32_16x16x32_bf16 v[0:3], v[96:99], v[80:83], 0
	v_mfma_f32_16x16x32_bf16 v[4:7], v[96:99], v[84:87], 0
	v_mfma_f32_16x16x32_bf16 v[8:11], v[96:99], v[88:91], 0
	v_mfma_f32_16x16x32_bf16 v[12:15], v[96:99], v[92:95], 0
	v_mfma_f32_16x16x32_bf16 v[16:19], v[100:103], v[80:83], 0
	v_mfma_f32_16x16x32_bf16 v[20:23], v[100:103], v[84:87], 0
	v_mfma_f32_16x16x32_bf16 v[24:27], v[100:103], v[88:91], 0
	v_mfma_f32_16x16x32_bf16 v[28:31], v[100:103], v[92:95], 0
	v_mfma_f32_16x16x32_bf16 v[32:35], v[104:107], v[80:83], 0
	v_mfma_f32_16x16x32_bf16 v[36:39], v[104:107], v[84:87], 0
	v_mfma_f32_16x16x32_bf16 v[40:43], v[104:107], v[88:91], 0
	v_mfma_f32_16x16x32_bf16 v[44:47], v[104:107], v[92:95], 0
	v_mfma_f32_16x16x32_bf16 v[48:51], v[108:111], v[80:83], 0
	v_mfma_f32_16x16x32_bf16 v[52:55], v[108:111], v[84:87], 0
	v_mfma_f32_16x16x32_bf16 v[56:59], v[108:111], v[88:91], 0
	v_mfma_f32_16x16x32_bf16 v[60:63], v[108:111], v[92:95], 0
	v_mfma_f32_16x16x32_bf16 v[64:67], v[112:115], v[80:83], 0
	v_mfma_f32_16x16x32_bf16 v[68:71], v[112:115], v[84:87], 0
	v_mfma_f32_16x16x32_bf16 v[72:75], v[112:115], v[88:91], 0
	v_mfma_f32_16x16x32_bf16 v[76:79], v[112:115], v[92:95], 0
	global_load_dwordx4 v[80:83], v180, s[18:19] offset:192
	global_load_dwordx4 v[84:87], v180, s[20:21] offset:192
	global_load_dwordx4 v[88:91], v180, s[22:23] offset:192
	global_load_dwordx4 v[92:95], v180, s[24:25] offset:192
	global_load_dwordx4 v[96:99], v180, s[36:37] offset:192
	global_load_dwordx4 v[100:103], v180, s[38:39] offset:192
	global_load_dwordx4 v[104:107], v180, s[40:41] offset:192
	global_load_dwordx4 v[108:111], v180, s[42:43] offset:192
	global_load_dwordx4 v[112:115], v180, s[44:45] offset:192
	s_waitcnt vmcnt(18)
	v_mfma_f32_16x16x32_bf16 v[0:3], v[132:135], v[116:119], v[0:3]
	v_mfma_f32_16x16x32_bf16 v[4:7], v[132:135], v[120:123], v[4:7]
	v_mfma_f32_16x16x32_bf16 v[8:11], v[132:135], v[124:127], v[8:11]
	v_mfma_f32_16x16x32_bf16 v[12:15], v[132:135], v[128:131], v[12:15]
	v_mfma_f32_16x16x32_bf16 v[16:19], v[136:139], v[116:119], v[16:19]
	v_mfma_f32_16x16x32_bf16 v[20:23], v[136:139], v[120:123], v[20:23]
	v_mfma_f32_16x16x32_bf16 v[24:27], v[136:139], v[124:127], v[24:27]
	v_mfma_f32_16x16x32_bf16 v[28:31], v[136:139], v[128:131], v[28:31]
	v_mfma_f32_16x16x32_bf16 v[32:35], v[140:143], v[116:119], v[32:35]
	v_mfma_f32_16x16x32_bf16 v[36:39], v[140:143], v[120:123], v[36:39]
	v_mfma_f32_16x16x32_bf16 v[40:43], v[140:143], v[124:127], v[40:43]
	v_mfma_f32_16x16x32_bf16 v[44:47], v[140:143], v[128:131], v[44:47]
	v_mfma_f32_16x16x32_bf16 v[48:51], v[144:147], v[116:119], v[48:51]
	v_mfma_f32_16x16x32_bf16 v[52:55], v[144:147], v[120:123], v[52:55]
	v_mfma_f32_16x16x32_bf16 v[56:59], v[144:147], v[124:127], v[56:59]
	v_mfma_f32_16x16x32_bf16 v[60:63], v[144:147], v[128:131], v[60:63]
	v_mfma_f32_16x16x32_bf16 v[64:67], v[148:151], v[116:119], v[64:67]
	v_mfma_f32_16x16x32_bf16 v[68:71], v[148:151], v[120:123], v[68:71]
	v_mfma_f32_16x16x32_bf16 v[72:75], v[148:151], v[124:127], v[72:75]
	v_mfma_f32_16x16x32_bf16 v[76:79], v[148:151], v[128:131], v[76:79]
	global_load_dwordx4 v[116:119], v180, s[18:19] offset:256
	global_load_dwordx4 v[120:123], v180, s[20:21] offset:256
	global_load_dwordx4 v[124:127], v180, s[22:23] offset:256
	global_load_dwordx4 v[128:131], v180, s[24:25] offset:256
	global_load_dwordx4 v[132:135], v180, s[36:37] offset:256
	global_load_dwordx4 v[136:139], v180, s[38:39] offset:256
	global_load_dwordx4 v[140:143], v180, s[40:41] offset:256
	global_load_dwordx4 v[144:147], v180, s[42:43] offset:256
	global_load_dwordx4 v[148:151], v180, s[44:45] offset:256
	s_waitcnt vmcnt(18)
	v_mfma_f32_16x16x32_bf16 v[0:3], v[168:171], v[152:155], v[0:3]
	v_mfma_f32_16x16x32_bf16 v[4:7], v[168:171], v[156:159], v[4:7]
	v_mfma_f32_16x16x32_bf16 v[8:11], v[168:171], v[160:163], v[8:11]
	v_mfma_f32_16x16x32_bf16 v[12:15], v[168:171], v[164:167], v[12:15]
	v_mfma_f32_16x16x32_bf16 v[16:19], v[172:175], v[152:155], v[16:19]
	v_mfma_f32_16x16x32_bf16 v[20:23], v[172:175], v[156:159], v[20:23]
	v_mfma_f32_16x16x32_bf16 v[24:27], v[172:175], v[160:163], v[24:27]
	v_mfma_f32_16x16x32_bf16 v[28:31], v[172:175], v[164:167], v[28:31]
	v_mfma_f32_16x16x32_bf16 v[32:35], v[176:179], v[152:155], v[32:35]
	v_mfma_f32_16x16x32_bf16 v[36:39], v[176:179], v[156:159], v[36:39]
	v_mfma_f32_16x16x32_bf16 v[40:43], v[176:179], v[160:163], v[40:43]
	v_mfma_f32_16x16x32_bf16 v[44:47], v[176:179], v[164:167], v[44:47]
	v_mfma_f32_16x16x32_bf16 v[48:51], v[188:191], v[152:155], v[48:51]
	v_mfma_f32_16x16x32_bf16 v[52:55], v[188:191], v[156:159], v[52:55]
	v_mfma_f32_16x16x32_bf16 v[56:59], v[188:191], v[160:163], v[56:59]
	v_mfma_f32_16x16x32_bf16 v[60:63], v[188:191], v[164:167], v[60:63]
	v_mfma_f32_16x16x32_bf16 v[64:67], v[192:195], v[152:155], v[64:67]
	v_mfma_f32_16x16x32_bf16 v[68:71], v[192:195], v[156:159], v[68:71]
	v_mfma_f32_16x16x32_bf16 v[72:75], v[192:195], v[160:163], v[72:75]
	v_mfma_f32_16x16x32_bf16 v[76:79], v[192:195], v[164:167], v[76:79]
	global_load_dwordx4 v[152:155], v180, s[18:19] offset:320
	global_load_dwordx4 v[156:159], v180, s[20:21] offset:320
	global_load_dwordx4 v[160:163], v180, s[22:23] offset:320
	global_load_dwordx4 v[164:167], v180, s[24:25] offset:320
	global_load_dwordx4 v[168:171], v180, s[36:37] offset:320
	global_load_dwordx4 v[172:175], v180, s[38:39] offset:320
	global_load_dwordx4 v[176:179], v180, s[40:41] offset:320
	global_load_dwordx4 v[188:191], v180, s[42:43] offset:320
	global_load_dwordx4 v[192:195], v180, s[44:45] offset:320
	s_waitcnt vmcnt(18)
	v_mfma_f32_16x16x32_bf16 v[0:3], v[96:99], v[80:83], v[0:3]
	v_mfma_f32_16x16x32_bf16 v[4:7], v[96:99], v[84:87], v[4:7]
	v_mfma_f32_16x16x32_bf16 v[8:11], v[96:99], v[88:91], v[8:11]
	v_mfma_f32_16x16x32_bf16 v[12:15], v[96:99], v[92:95], v[12:15]
	v_mfma_f32_16x16x32_bf16 v[16:19], v[100:103], v[80:83], v[16:19]
	v_mfma_f32_16x16x32_bf16 v[20:23], v[100:103], v[84:87], v[20:23]
	v_mfma_f32_16x16x32_bf16 v[24:27], v[100:103], v[88:91], v[24:27]
	v_mfma_f32_16x16x32_bf16 v[28:31], v[100:103], v[92:95], v[28:31]
	v_mfma_f32_16x16x32_bf16 v[32:35], v[104:107], v[80:83], v[32:35]
	v_mfma_f32_16x16x32_bf16 v[36:39], v[104:107], v[84:87], v[36:39]
	v_mfma_f32_16x16x32_bf16 v[40:43], v[104:107], v[88:91], v[40:43]
	v_mfma_f32_16x16x32_bf16 v[44:47], v[104:107], v[92:95], v[44:47]
	v_mfma_f32_16x16x32_bf16 v[48:51], v[108:111], v[80:83], v[48:51]
	v_mfma_f32_16x16x32_bf16 v[52:55], v[108:111], v[84:87], v[52:55]
	v_mfma_f32_16x16x32_bf16 v[56:59], v[108:111], v[88:91], v[56:59]
	v_mfma_f32_16x16x32_bf16 v[60:63], v[108:111], v[92:95], v[60:63]
	v_mfma_f32_16x16x32_bf16 v[64:67], v[112:115], v[80:83], v[64:67]
	v_mfma_f32_16x16x32_bf16 v[68:71], v[112:115], v[84:87], v[68:71]
	v_mfma_f32_16x16x32_bf16 v[72:75], v[112:115], v[88:91], v[72:75]
	v_mfma_f32_16x16x32_bf16 v[76:79], v[112:115], v[92:95], v[76:79]
	global_load_dwordx4 v[80:83], v180, s[18:19] offset:384
	global_load_dwordx4 v[84:87], v180, s[20:21] offset:384
	global_load_dwordx4 v[88:91], v180, s[22:23] offset:384
	global_load_dwordx4 v[92:95], v180, s[24:25] offset:384
	global_load_dwordx4 v[96:99], v180, s[36:37] offset:384
	global_load_dwordx4 v[100:103], v180, s[38:39] offset:384
	global_load_dwordx4 v[104:107], v180, s[40:41] offset:384
	global_load_dwordx4 v[108:111], v180, s[42:43] offset:384
	global_load_dwordx4 v[112:115], v180, s[44:45] offset:384
	s_waitcnt vmcnt(18)
	v_mfma_f32_16x16x32_bf16 v[0:3], v[132:135], v[116:119], v[0:3]
	v_mfma_f32_16x16x32_bf16 v[4:7], v[132:135], v[120:123], v[4:7]
	v_mfma_f32_16x16x32_bf16 v[8:11], v[132:135], v[124:127], v[8:11]
	v_mfma_f32_16x16x32_bf16 v[12:15], v[132:135], v[128:131], v[12:15]
	v_mfma_f32_16x16x32_bf16 v[16:19], v[136:139], v[116:119], v[16:19]
	v_mfma_f32_16x16x32_bf16 v[20:23], v[136:139], v[120:123], v[20:23]
	v_mfma_f32_16x16x32_bf16 v[24:27], v[136:139], v[124:127], v[24:27]
	v_mfma_f32_16x16x32_bf16 v[28:31], v[136:139], v[128:131], v[28:31]
	v_mfma_f32_16x16x32_bf16 v[32:35], v[140:143], v[116:119], v[32:35]
	v_mfma_f32_16x16x32_bf16 v[36:39], v[140:143], v[120:123], v[36:39]
	v_mfma_f32_16x16x32_bf16 v[40:43], v[140:143], v[124:127], v[40:43]
	v_mfma_f32_16x16x32_bf16 v[44:47], v[140:143], v[128:131], v[44:47]
	v_mfma_f32_16x16x32_bf16 v[48:51], v[144:147], v[116:119], v[48:51]
	v_mfma_f32_16x16x32_bf16 v[52:55], v[144:147], v[120:123], v[52:55]
	v_mfma_f32_16x16x32_bf16 v[56:59], v[144:147], v[124:127], v[56:59]
	v_mfma_f32_16x16x32_bf16 v[60:63], v[144:147], v[128:131], v[60:63]
	v_mfma_f32_16x16x32_bf16 v[64:67], v[148:151], v[116:119], v[64:67]
	v_mfma_f32_16x16x32_bf16 v[68:71], v[148:151], v[120:123], v[68:71]
	v_mfma_f32_16x16x32_bf16 v[72:75], v[148:151], v[124:127], v[72:75]
	v_mfma_f32_16x16x32_bf16 v[76:79], v[148:151], v[128:131], v[76:79]
	global_load_dwordx4 v[116:119], v180, s[18:19] offset:448
	global_load_dwordx4 v[120:123], v180, s[20:21] offset:448
	global_load_dwordx4 v[124:127], v180, s[22:23] offset:448
	global_load_dwordx4 v[128:131], v180, s[24:25] offset:448
	global_load_dwordx4 v[132:135], v180, s[36:37] offset:448
	global_load_dwordx4 v[136:139], v180, s[38:39] offset:448
	global_load_dwordx4 v[140:143], v180, s[40:41] offset:448
	global_load_dwordx4 v[144:147], v180, s[42:43] offset:448
	global_load_dwordx4 v[148:151], v180, s[44:45] offset:448
	s_waitcnt vmcnt(18)
	v_mfma_f32_16x16x32_bf16 v[0:3], v[168:171], v[152:155], v[0:3]
	v_mfma_f32_16x16x32_bf16 v[4:7], v[168:171], v[156:159], v[4:7]
	v_mfma_f32_16x16x32_bf16 v[8:11], v[168:171], v[160:163], v[8:11]
	v_mfma_f32_16x16x32_bf16 v[12:15], v[168:171], v[164:167], v[12:15]
	v_mfma_f32_16x16x32_bf16 v[16:19], v[172:175], v[152:155], v[16:19]
	v_mfma_f32_16x16x32_bf16 v[20:23], v[172:175], v[156:159], v[20:23]
	v_mfma_f32_16x16x32_bf16 v[24:27], v[172:175], v[160:163], v[24:27]
	v_mfma_f32_16x16x32_bf16 v[28:31], v[172:175], v[164:167], v[28:31]
	v_mfma_f32_16x16x32_bf16 v[32:35], v[176:179], v[152:155], v[32:35]
	v_mfma_f32_16x16x32_bf16 v[36:39], v[176:179], v[156:159], v[36:39]
	v_mfma_f32_16x16x32_bf16 v[40:43], v[176:179], v[160:163], v[40:43]
	v_mfma_f32_16x16x32_bf16 v[44:47], v[176:179], v[164:167], v[44:47]
	v_mfma_f32_16x16x32_bf16 v[48:51], v[188:191], v[152:155], v[48:51]
	v_mfma_f32_16x16x32_bf16 v[52:55], v[188:191], v[156:159], v[52:55]
	v_mfma_f32_16x16x32_bf16 v[56:59], v[188:191], v[160:163], v[56:59]
	v_mfma_f32_16x16x32_bf16 v[60:63], v[188:191], v[164:167], v[60:63]
	v_mfma_f32_16x16x32_bf16 v[64:67], v[192:195], v[152:155], v[64:67]
	v_mfma_f32_16x16x32_bf16 v[68:71], v[192:195], v[156:159], v[68:71]
	v_mfma_f32_16x16x32_bf16 v[72:75], v[192:195], v[160:163], v[72:75]
	v_mfma_f32_16x16x32_bf16 v[76:79], v[192:195], v[164:167], v[76:79]
	s_waitcnt vmcnt(9)
	v_mfma_f32_16x16x32_bf16 v[0:3], v[96:99], v[80:83], v[0:3]
	v_mfma_f32_16x16x32_bf16 v[4:7], v[96:99], v[84:87], v[4:7]
	v_mfma_f32_16x16x32_bf16 v[8:11], v[96:99], v[88:91], v[8:11]
	v_mfma_f32_16x16x32_bf16 v[12:15], v[96:99], v[92:95], v[12:15]
	v_mfma_f32_16x16x32_bf16 v[16:19], v[100:103], v[80:83], v[16:19]
	v_mfma_f32_16x16x32_bf16 v[20:23], v[100:103], v[84:87], v[20:23]
	v_mfma_f32_16x16x32_bf16 v[24:27], v[100:103], v[88:91], v[24:27]
	v_mfma_f32_16x16x32_bf16 v[28:31], v[100:103], v[92:95], v[28:31]
	v_mfma_f32_16x16x32_bf16 v[32:35], v[104:107], v[80:83], v[32:35]
	v_mfma_f32_16x16x32_bf16 v[36:39], v[104:107], v[84:87], v[36:39]
	v_mfma_f32_16x16x32_bf16 v[40:43], v[104:107], v[88:91], v[40:43]
	v_mfma_f32_16x16x32_bf16 v[44:47], v[104:107], v[92:95], v[44:47]
	v_mfma_f32_16x16x32_bf16 v[48:51], v[108:111], v[80:83], v[48:51]
	v_mfma_f32_16x16x32_bf16 v[52:55], v[108:111], v[84:87], v[52:55]
	v_mfma_f32_16x16x32_bf16 v[56:59], v[108:111], v[88:91], v[56:59]
	v_mfma_f32_16x16x32_bf16 v[60:63], v[108:111], v[92:95], v[60:63]
	v_mfma_f32_16x16x32_bf16 v[64:67], v[112:115], v[80:83], v[64:67]
	v_mfma_f32_16x16x32_bf16 v[68:71], v[112:115], v[84:87], v[68:71]
	v_mfma_f32_16x16x32_bf16 v[72:75], v[112:115], v[88:91], v[72:75]
	v_mfma_f32_16x16x32_bf16 v[76:79], v[112:115], v[92:95], v[76:79]
	s_waitcnt vmcnt(0)
	v_mfma_f32_16x16x32_bf16 v[0:3], v[132:135], v[116:119], v[0:3]
	v_mfma_f32_16x16x32_bf16 v[4:7], v[132:135], v[120:123], v[4:7]
	v_mfma_f32_16x16x32_bf16 v[8:11], v[132:135], v[124:127], v[8:11]
	v_mfma_f32_16x16x32_bf16 v[12:15], v[132:135], v[128:131], v[12:15]
	v_mfma_f32_16x16x32_bf16 v[16:19], v[136:139], v[116:119], v[16:19]
	v_mfma_f32_16x16x32_bf16 v[20:23], v[136:139], v[120:123], v[20:23]
	v_mfma_f32_16x16x32_bf16 v[24:27], v[136:139], v[124:127], v[24:27]
	v_mfma_f32_16x16x32_bf16 v[28:31], v[136:139], v[128:131], v[28:31]
	v_mfma_f32_16x16x32_bf16 v[32:35], v[140:143], v[116:119], v[32:35]
	v_mfma_f32_16x16x32_bf16 v[36:39], v[140:143], v[120:123], v[36:39]
	v_mfma_f32_16x16x32_bf16 v[40:43], v[140:143], v[124:127], v[40:43]
	v_mfma_f32_16x16x32_bf16 v[44:47], v[140:143], v[128:131], v[44:47]
	v_mfma_f32_16x16x32_bf16 v[48:51], v[144:147], v[116:119], v[48:51]
	v_mfma_f32_16x16x32_bf16 v[52:55], v[144:147], v[120:123], v[52:55]
	v_mfma_f32_16x16x32_bf16 v[56:59], v[144:147], v[124:127], v[56:59]
	v_mfma_f32_16x16x32_bf16 v[60:63], v[144:147], v[128:131], v[60:63]
	v_mfma_f32_16x16x32_bf16 v[64:67], v[148:151], v[116:119], v[64:67]
	v_mfma_f32_16x16x32_bf16 v[68:71], v[148:151], v[120:123], v[68:71]
	v_mfma_f32_16x16x32_bf16 v[72:75], v[148:151], v[124:127], v[72:75]
	v_mfma_f32_16x16x32_bf16 v[76:79], v[148:151], v[128:131], v[76:79]
	s_nop 7
	s_nop 7
	s_nop 7
	s_cmp_lt_u32 s15, 4
	s_cbranch_scc1 .Lmg_lo
; template <class Epi, class Sched, bool ALIGN_EPI = false, bool SP2 = false>
; __device__ __forceinline__ void gemm_phase(PG8_LAS unsigned char* lds, const Gemm g, const Sched& S, const Epi& E, const int wid_in) {
;     ...
;         if constexpr (!Epi::AFTER_DRAIN) { E(acc, cur, wr, wc, fr, fq); S.done(cur); }
	s_sub_i32 s0, s15, 4
	s_mulk_i32 s0, 0x5000
	v_add_u32_e32 v204, s0, v181
	ds_write_b128 v204, v[0:3] offset:0
	ds_write_b128 v204, v[4:7] offset:1024
	ds_write_b128 v204, v[8:11] offset:2048
	ds_write_b128 v204, v[12:15] offset:3072
	ds_write_b128 v204, v[16:19] offset:4096
	ds_write_b128 v204, v[20:23] offset:5120
	ds_write_b128 v204, v[24:27] offset:6144
	ds_write_b128 v204, v[28:31] offset:7168
	ds_write_b128 v204, v[32:35] offset:8192
	ds_write_b128 v204, v[36:39] offset:9216
	ds_write_b128 v204, v[40:43] offset:10240
	ds_write_b128 v204, v[44:47] offset:11264
	ds_write_b128 v204, v[48:51] offset:12288
	ds_write_b128 v204, v[52:55] offset:13312
	ds_write_b128 v204, v[56:59] offset:14336
	ds_write_b128 v204, v[60:63] offset:15360
	ds_write_b128 v204, v[64:67] offset:16384
	ds_write_b128 v204, v[68:71] offset:17408
	ds_write_b128 v204, v[72:75] offset:18432
	ds_write_b128 v204, v[76:79] offset:19456
	s_waitcnt lgkmcnt(0)
	s_barrier
	s_barrier
	s_branch .Lmg_fin
.Lmg_lo:
	s_mul_i32 s0, s15, 0x5000
	v_add_u32_e32 v204, s0, v181
	s_barrier
	ds_read_b128 v[80:83], v204 offset:0
	ds_read_b128 v[84:87], v204 offset:1024
	ds_read_b128 v[88:91], v204 offset:2048
	ds_read_b128 v[92:95], v204 offset:3072
	ds_read_b128 v[96:99], v204 offset:4096
	ds_read_b128 v[100:103], v204 offset:5120
	ds_read_b128 v[104:107], v204 offset:6144
	ds_read_b128 v[108:111], v204 offset:7168
	ds_read_b128 v[112:115], v204 offset:8192
	ds_read_b128 v[116:119], v204 offset:9216
	ds_read_b128 v[120:123], v204 offset:10240
	ds_read_b128 v[124:127], v204 offset:11264
	ds_read_b128 v[128:131], v204 offset:12288
	ds_read_b128 v[132:135], v204 offset:13312
	ds_read_b128 v[136:139], v204 offset:14336
	ds_read_b128 v[140:143], v204 offset:15360
	ds_read_b128 v[144:147], v204 offset:16384
	ds_read_b128 v[148:151], v204 offset:17408
	ds_read_b128 v[152:155], v204 offset:18432
	ds_read_b128 v[156:159], v204 offset:19456
	s_waitcnt lgkmcnt(0)
	v_pk_add_f32 v[0:1], v[0:1], v[80:81]
	v_pk_add_f32 v[2:3], v[2:3], v[82:83]
	v_pk_add_f32 v[4:5], v[4:5], v[84:85]
	v_pk_add_f32 v[6:7], v[6:7], v[86:87]
	v_pk_add_f32 v[8:9], v[8:9], v[88:89]
	v_pk_add_f32 v[10:11], v[10:11], v[90:91]
	v_pk_add_f32 v[12:13], v[12:13], v[92:93]
	v_pk_add_f32 v[14:15], v[14:15], v[94:95]
	v_pk_add_f32 v[16:17], v[16:17], v[96:97]
	v_pk_add_f32 v[18:19], v[18:19], v[98:99]
	v_pk_add_f32 v[20:21], v[20:21], v[100:101]
	v_pk_add_f32 v[22:23], v[22:23], v[102:103]
	v_pk_add_f32 v[24:25], v[24:25], v[104:105]
	v_pk_add_f32 v[26:27], v[26:27], v[106:107]
	v_pk_add_f32 v[28:29], v[28:29], v[108:109]
	v_pk_add_f32 v[30:31], v[30:31], v[110:111]
	v_pk_add_f32 v[32:33], v[32:33], v[112:113]
	v_pk_add_f32 v[34:35], v[34:35], v[114:115]
	v_pk_add_f32 v[36:37], v[36:37], v[116:117]
	v_pk_add_f32 v[38:39], v[38:39], v[118:119]
	v_pk_add_f32 v[40:41], v[40:41], v[120:121]
	v_pk_add_f32 v[42:43], v[42:43], v[122:123]
	v_pk_add_f32 v[44:45], v[44:45], v[124:125]
	v_pk_add_f32 v[46:47], v[46:47], v[126:127]
	v_pk_add_f32 v[48:49], v[48:49], v[128:129]
	v_pk_add_f32 v[50:51], v[50:51], v[130:131]
	v_pk_add_f32 v[52:53], v[52:53], v[132:133]
	v_pk_add_f32 v[54:55], v[54:55], v[134:135]
	v_pk_add_f32 v[56:57], v[56:57], v[136:137]
	v_pk_add_f32 v[58:59], v[58:59], v[138:139]
	v_pk_add_f32 v[60:61], v[60:61], v[140:141]
	v_pk_add_f32 v[62:63], v[62:63], v[142:143]
	v_pk_add_f32 v[64:65], v[64:65], v[144:145]
	v_pk_add_f32 v[66:67], v[66:67], v[146:147]
	v_pk_add_f32 v[68:69], v[68:69], v[148:149]
	v_pk_add_f32 v[70:71], v[70:71], v[150:151]
	v_pk_add_f32 v[72:73], v[72:73], v[152:153]
	v_pk_add_f32 v[74:75], v[74:75], v[154:155]
	v_pk_add_f32 v[76:77], v[76:77], v[156:157]
	v_pk_add_f32 v[78:79], v[78:79], v[158:159]
	ds_write_b128 v204, v[0:3] offset:0
	ds_write_b128 v204, v[4:7] offset:1024
	ds_write_b128 v204, v[8:11] offset:2048
	ds_write_b128 v204, v[12:15] offset:3072
	ds_write_b128 v204, v[16:19] offset:4096
	ds_write_b128 v204, v[20:23] offset:5120
	ds_write_b128 v204, v[24:27] offset:6144
	ds_write_b128 v204, v[28:31] offset:7168
	ds_write_b128 v204, v[32:35] offset:8192
	ds_write_b128 v204, v[36:39] offset:9216
	ds_write_b128 v204, v[40:43] offset:10240
	ds_write_b128 v204, v[44:47] offset:11264
	ds_write_b128 v204, v[48:51] offset:12288
	ds_write_b128 v204, v[52:55] offset:13312
	ds_write_b128 v204, v[56:59] offset:14336
	ds_write_b128 v204, v[60:63] offset:15360
	ds_write_b128 v204, v[64:67] offset:16384
	ds_write_b128 v204, v[68:71] offset:17408
	ds_write_b128 v204, v[72:75] offset:18432
	ds_write_b128 v204, v[76:79] offset:19456
	s_waitcnt lgkmcnt(0)
	s_barrier
; __device__ __forceinline__ unsigned cvt_pk_bf16(float lo, float hi) { unsigned r; asm volatile("v_cvt_pk_bf16_f32 %0, %1, %2" : "=v"(r) : "v"(lo), "v"(hi)); return r; }
;     __device__ __forceinline__ void operator()(const f32x4 (&acc)[2][2][4][2], const Unit& u, int wr, int wc, int fr, int fq) const {
;         const int row0 = u.pm * BM + wr * 64 + fr; const int colt = u.pn * BM;
;         const float sc = (colt < scale_cols) ? scale0 : 1.f;
;         const int col0 = colt + wc * 32 + 8 * fq;
; #pragma unroll
;         for (int ai = 0; ai < 2; ++ai)
; #pragma unroll
;             for (int m = 0; m < 4; ++m) { bf16_t* rowp = O + (size_t)(row0 + ai * HALF + m * 16) * ldc + col0;
;                 const float rs = rowss ? sc * (1.0f / sqrtf((float)__hip_atomic_load(rowss + row0 + ai * HALF + m * 16, __ATOMIC_RELAXED, __HIP_MEMORY_SCOPE_AGENT) * (1.0f / (2048.0f * 1048576.0f)) + 1e-6f)) : sc;
; #pragma unroll
;                 for (int bj = 0; bj < 2; ++bj) { f32x4 v0 = acc[ai][bj][m][0] * rs, v1 = acc[ai][bj][m][1] * rs;
;                     if (ACT == 1) {
; #pragma unroll
;                         for (int e = 0; e < 4; ++e) { float a = v0[e] > 0.f ? v0[e] : 0.f; v0[e] = a * a; float b = v1[e] > 0.f ? v1[e] : 0.f; v1[e] = b * b; } }
;                     u32x4 w; w.x = cvt_pk_bf16(v0[0], v0[1]); w.y = cvt_pk_bf16(v0[2], v0[3]); w.z = cvt_pk_bf16(v1[0], v1[1]); w.w = cvt_pk_bf16(v1[2], v1[3]);
;                     *(u32x4*)(rowp + bj * HALF) = w; } }
.Lmg_fin:
	s_lshl_b32 s0, s15, 10
	v_add_u32_e32 v204, s0, v181
	v_add_u32_e32 v205, 0xf000, v204
	ds_read_b128 v[80:83], v204 offset:0
	ds_read_b128 v[84:87], v204 offset:20480
	ds_read_b128 v[88:91], v204 offset:40960
	ds_read_b128 v[92:95], v205 offset:0
	ds_read_b128 v[96:99], v204 offset:8192
	ds_read_b128 v[100:103], v204 offset:28672
	ds_read_b128 v[104:107], v204 offset:49152
	ds_read_b128 v[108:111], v205 offset:8192
	ds_read_b128 v[112:115], v204 offset:16384
	ds_read_b128 v[116:119], v204 offset:36864
	ds_read_b128 v[120:123], v204 offset:57344
	ds_read_b128 v[124:127], v205 offset:16384
	s_waitcnt vmcnt(0)
	v_ffbh_u32_e32 v220, v219
	v_min_u32_e32 v220, 32, v220
	v_lshlrev_b64 v[218:219], v220, v[218:219]
	v_min_u32_e32 v218, 1, v218
	v_or_b32_e32 v218, v219, v218
	v_cvt_f32_u32_e32 v218, v218
	v_sub_u32_e32 v219, 32, v220
	v_ldexp_f32 v218, v218, v219
	v_fmamk_f32 v218, v218, 0x30000000, v208
	v_mul_f32_e32 v219, 0x4f800000, v218
	v_cmp_gt_f32_e32 vcc, s33, v218
	s_nop 1
	v_cndmask_b32_e32 v218, v218, v219, vcc
	v_sqrt_f32_e32 v219, v218
	s_nop 0
	v_add_u32_e32 v220, -1, v219
	v_add_u32_e32 v221, 1, v219
	v_fma_f32 v222, -v220, v219, v218
	v_fma_f32 v223, -v221, v219, v218
	v_cmp_ge_f32_e64 s[6:7], 0, v222
	s_nop 1
	v_cndmask_b32_e64 v219, v219, v220, s[6:7]
	v_cmp_lt_f32_e64 s[6:7], 0, v223
	s_nop 1
	v_cndmask_b32_e64 v219, v219, v221, s[6:7]
	v_mul_f32_e32 v220, 0x37800000, v219
	v_cndmask_b32_e32 v219, v219, v220, vcc
	v_cmp_class_f32_e32 vcc, v218, v209
	s_nop 1
	v_cndmask_b32_e32 v218, v219, v218, vcc
	v_div_scale_f32 v219, s[6:7], v218, v218, 1.0
	v_rcp_f32_e32 v220, v219
	v_div_scale_f32 v221, vcc, 1.0, v218, 1.0
	v_fma_f32 v222, -v219, v220, 1.0
	v_fmac_f32_e32 v220, v222, v220
	v_mul_f32_e32 v222, v221, v220
	v_fma_f32 v223, -v219, v222, v221
	v_fmac_f32_e32 v222, v223, v220
	v_fma_f32 v219, -v219, v222, v221
	v_div_fmas_f32 v219, v219, v220, v222
	v_div_fixup_f32 v224, v219, v218, 1.0
	v_mul_u32_u24_e32 v216, 0x2200, v214
	s_lshr_b32 s0, s15, 2
	s_lshl_b32 s0, s0, 5
	s_addk_i32 s0, 0x2000
	v_lshrrev_b32_e32 v215, 4, v206
	v_lshl_add_u32 v216, v215, 3, v216
	v_add_u32_e32 v216, s0, v216
	s_waitcnt lgkmcnt(0)
	v_pk_add_f32 v[80:81], v[80:81], v[84:85]
	v_pk_add_f32 v[82:83], v[82:83], v[86:87]
	v_pk_add_f32 v[88:89], v[88:89], v[92:93]
	v_pk_add_f32 v[90:91], v[90:91], v[94:95]
	v_pk_add_f32 v[80:81], v[80:81], v[88:89]
	v_pk_add_f32 v[82:83], v[82:83], v[90:91]
	v_pk_mul_f32 v[80:81], v[80:81], v[224:225] op_sel_hi:[1,0]
	v_pk_mul_f32 v[82:83], v[82:83], v[224:225] op_sel_hi:[1,0]
	v_cvt_pk_bf16_f32 v226, v80, v81
	v_cvt_pk_bf16_f32 v227, v82, v83
	global_store_dwordx2 v216, v[226:227], s[78:79] offset:0
	v_pk_add_f32 v[96:97], v[96:97], v[100:101]
	v_pk_add_f32 v[98:99], v[98:99], v[102:103]
	v_pk_add_f32 v[104:105], v[104:105], v[108:109]
	v_pk_add_f32 v[106:107], v[106:107], v[110:111]
	v_pk_add_f32 v[96:97], v[96:97], v[104:105]
	v_pk_add_f32 v[98:99], v[98:99], v[106:107]
	v_pk_mul_f32 v[96:97], v[96:97], v[224:225] op_sel_hi:[1,0]
	v_pk_mul_f32 v[98:99], v[98:99], v[224:225] op_sel_hi:[1,0]
	v_cvt_pk_bf16_f32 v228, v96, v97
	v_cvt_pk_bf16_f32 v229, v98, v99
	global_store_dwordx2 v216, v[228:229], s[78:79] offset:64
	s_cmp_ge_u32 s15, 4
	s_cbranch_scc1 .Lmg_skip3
	v_pk_add_f32 v[112:113], v[112:113], v[116:117]
	v_pk_add_f32 v[114:115], v[114:115], v[118:119]
	v_pk_add_f32 v[120:121], v[120:121], v[124:125]
	v_pk_add_f32 v[122:123], v[122:123], v[126:127]
	v_pk_add_f32 v[112:113], v[112:113], v[120:121]
	v_pk_add_f32 v[114:115], v[114:115], v[122:123]
	v_pk_mul_f32 v[112:113], v[112:113], v[224:225] op_sel_hi:[1,0]
	v_pk_mul_f32 v[114:115], v[114:115], v[224:225] op_sel_hi:[1,0]
	v_cvt_pk_bf16_f32 v230, v112, v113
	v_cvt_pk_bf16_f32 v231, v114, v115
	global_store_dwordx2 v216, v[230:231], s[78:79] offset:128
.Lmg_skip3:
	s_add_i32 s14, s14, s64
	s_barrier
	s_branch .Lmg_unit
.Lmg_done:
.LBB0_156:
	s_mov_b64 s[0:1], 0
